# pairk2 with static s_setprio 1 for waves 0-3 instead of 4-7
# speedup vs baseline: 1.0114x; 1.0114x over previous
_Z14fwd_megakernel4Args:
	v_readfirstlane_b32 s98, v0
	s_bfe_u32 s98, s98, 0x10008
	s_cmp_eq_u32 s98, 0
	s_cbranch_scc0 .Lprio_done
	s_setprio 1
